# v014 + attention: QK accumulators land directly in the registers the softmax reads (16 copies per tile removed)
# speedup vs baseline: 1.0054x; 1.0054x over previous
.LBB0_2765:
	s_andn2_b64 vcc, exec, s[8:9]
	s_cbranch_vccnz .LBB0_2775
	s_and_b32 s22, s21, 0x8000
	v_ashrrev_i32_e32 v16, 5, v242
	v_and_b32_e32 v2, 31, v242
	s_add_i32 s8, s43, s22
	v_lshlrev_b32_e32 v17, 4, v16
	v_lshlrev_b32_e32 v253, 4, v242
	v_and_b32_e32 v190, 0x70, v253
	v_lshl_add_u32 v191, v2, 8, s8
	v_add_u32_e32 v12, 32, v17
	v_xad_u32 v8, v17, v190, v191
	v_xad_u32 v178, v12, v190, v191
	ds_read_b128 v[4:7], v8
	ds_read_b128 v[8:11], v8 offset:8192
	ds_read_b128 v[12:15], v178
	ds_read_b128 v[178:181], v178 offset:8192
	v_add_u32_e32 v182, 64, v17
	v_xad_u32 v186, v182, v190, v191
	ds_read_b128 v[182:185], v186
	ds_read_b128 v[186:189], v186 offset:8192
	s_waitcnt lgkmcnt(0)
	v_mfma_f32_32x32x16_bf16 v[162:177], v[4:7], v[210:213], 0
	v_mfma_f32_32x32x16_bf16 v[146:161], v[8:11], v[210:213], 0
	v_add_u32_e32 v4, 0x60, v17
	v_xad_u32 v8, v4, v190, v191
	ds_read_b128 v[4:7], v8
	ds_read_b128 v[8:11], v8 offset:8192
	v_mfma_f32_32x32x16_bf16 v[162:177], v[12:15], v[214:217], v[162:177]
	v_mfma_f32_32x32x16_bf16 v[146:161], v[178:181], v[214:217], v[146:161]
	v_add_u32_e32 v12, 0x80, v17
	v_xad_u32 v178, v12, v190, v191
	ds_read_b128 v[12:15], v178
	ds_read_b128 v[178:181], v178 offset:8192
	v_mfma_f32_32x32x16_bf16 v[162:177], v[182:185], v[218:221], v[162:177]
	v_mfma_f32_32x32x16_bf16 v[146:161], v[186:189], v[218:221], v[146:161]
	v_add_u32_e32 v182, 0xa0, v17
	v_xad_u32 v186, v182, v190, v191
	ds_read_b128 v[182:185], v186
	ds_read_b128 v[186:189], v186 offset:8192
	s_waitcnt lgkmcnt(0)
	v_mfma_f32_32x32x16_bf16 v[162:177], v[4:7], v[222:225], v[162:177]
	v_mfma_f32_32x32x16_bf16 v[146:161], v[8:11], v[222:225], v[146:161]
	v_add_u32_e32 v4, 0xc0, v17
	v_xad_u32 v8, v4, v190, v191
	ds_read_b128 v[4:7], v8
	ds_read_b128 v[8:11], v8 offset:8192
	v_mfma_f32_32x32x16_bf16 v[162:177], v[12:15], v[226:229], v[162:177]
	v_mfma_f32_32x32x16_bf16 v[146:161], v[178:181], v[226:229], v[146:161]
	v_add_u32_e32 v12, 0xe0, v17
	v_xad_u32 v17, v12, v190, v191
	ds_read_b128 v[12:15], v17
	ds_read_b128 v[178:181], v17 offset:8192
	v_mfma_f32_32x32x16_bf16 v[162:177], v[182:185], v[230:233], v[162:177]
	v_mfma_f32_32x32x16_bf16 v[146:161], v[186:189], v[230:233], v[146:161]
	s_waitcnt lgkmcnt(0)
	v_mfma_f32_32x32x16_bf16 v[162:177], v[4:7], v[234:237], v[162:177]
	v_mfma_f32_32x32x16_bf16 v[146:161], v[8:11], v[234:237], v[146:161]
	v_mfma_f32_32x32x16_bf16 v[162:177], v[12:15], v[238:241], v[162:177]
	v_mfma_f32_32x32x16_bf16 v[146:161], v[178:181], v[238:241], v[146:161]
	s_add_i32 s23, s18, s20
	s_add_i32 s10, s20, 63
	s_add_i32 s8, s23, 0xffffe0bf
	s_cmpk_lt_i32 s8, 0xffa6
	s_cselect_b64 s[8:9], -1, 0
	s_cmp_lt_i32 s10, s15
	s_cselect_b64 s[12:13], -1, 0
	s_and_b64 s[10:11], s[12:13], s[8:9]
	s_mov_b64 s[8:9], -1
	s_and_b64 vcc, exec, s[10:11]
	v_lshlrev_b32_e32 v11, 2, v16
	s_cbranch_vccnz .LBB0_2768
	v_sub_u32_e32 v2, v11, v2
	v_add_u32_e32 v2, s23, v2
	s_add_i32 s23, 0, 0x18600
	v_lshl_add_u32 v2, v2, 2, s23
	ds_read2_b32 v[178:179], v2 offset0:0 offset1:1
	ds_read2_b32 v[180:181], v2 offset0:2 offset1:3
	ds_read2_b32 v[182:183], v2 offset0:8 offset1:9
	ds_read2_b32 v[184:185], v2 offset0:10 offset1:11
	ds_read2_b32 v[186:187], v2 offset0:16 offset1:17
	ds_read2_b32 v[188:189], v2 offset0:18 offset1:19
	ds_read2_b32 v[190:191], v2 offset0:24 offset1:25
	ds_read2_b32 v[192:193], v2 offset0:26 offset1:27
	ds_read2_b32 v[194:195], v2 offset0:32 offset1:33
	ds_read2_b32 v[196:197], v2 offset0:34 offset1:35
	ds_read2_b32 v[198:199], v2 offset0:40 offset1:41
	ds_read2_b32 v[200:201], v2 offset0:42 offset1:43
	ds_read2_b32 v[202:203], v2 offset0:48 offset1:49
	ds_read2_b32 v[204:205], v2 offset0:50 offset1:51
	ds_read2_b32 v[206:207], v2 offset0:56 offset1:57
	ds_read2_b32 v[208:209], v2 offset0:58 offset1:59
	s_waitcnt lgkmcnt(0)
	v_fmamk_f32 v162, v162, 0x3e0293ee, v178
	v_fmamk_f32 v146, v146, 0x3e0293ee, v194
	v_fmamk_f32 v163, v163, 0x3e0293ee, v179
	v_fmamk_f32 v147, v147, 0x3e0293ee, v195
	v_max_f32_e32 v2, v162, v146
	v_fmamk_f32 v164, v164, 0x3e0293ee, v180
	v_fmamk_f32 v148, v148, 0x3e0293ee, v196
	v_max3_f32 v2, v2, v163, v147
	v_fmamk_f32 v165, v165, 0x3e0293ee, v181
	v_fmamk_f32 v149, v149, 0x3e0293ee, v197
	v_max3_f32 v2, v2, v164, v148
	v_fmamk_f32 v166, v166, 0x3e0293ee, v182
	v_fmamk_f32 v150, v150, 0x3e0293ee, v198
	v_max3_f32 v2, v2, v165, v149
	v_fmamk_f32 v167, v167, 0x3e0293ee, v183
	v_fmamk_f32 v151, v151, 0x3e0293ee, v199
	v_max3_f32 v2, v2, v166, v150
	v_fmamk_f32 v168, v168, 0x3e0293ee, v184
	v_fmamk_f32 v152, v152, 0x3e0293ee, v200
	v_max3_f32 v2, v2, v167, v151
	v_fmamk_f32 v169, v169, 0x3e0293ee, v185
	v_fmamk_f32 v153, v153, 0x3e0293ee, v201
	v_max3_f32 v2, v2, v168, v152
	v_fmamk_f32 v170, v170, 0x3e0293ee, v186
	v_fmamk_f32 v154, v154, 0x3e0293ee, v202
	v_max3_f32 v2, v2, v169, v153
	v_fmamk_f32 v171, v171, 0x3e0293ee, v187
	v_fmamk_f32 v155, v155, 0x3e0293ee, v203
	v_max3_f32 v2, v2, v170, v154
	v_fmamk_f32 v172, v172, 0x3e0293ee, v188
	v_fmamk_f32 v156, v156, 0x3e0293ee, v204
	v_max3_f32 v2, v2, v171, v155
	v_fmamk_f32 v173, v173, 0x3e0293ee, v189
	v_fmamk_f32 v157, v157, 0x3e0293ee, v205
	v_max3_f32 v2, v2, v172, v156
	v_fmamk_f32 v174, v174, 0x3e0293ee, v190
	v_fmamk_f32 v158, v158, 0x3e0293ee, v206
	v_max3_f32 v2, v2, v173, v157
	v_fmamk_f32 v175, v175, 0x3e0293ee, v191
	v_fmamk_f32 v159, v159, 0x3e0293ee, v207
	v_max3_f32 v2, v2, v174, v158
	v_fmamk_f32 v176, v176, 0x3e0293ee, v192
	v_fmamk_f32 v160, v160, 0x3e0293ee, v208
	v_max3_f32 v2, v2, v175, v159
	v_fmamk_f32 v177, v177, 0x3e0293ee, v193
	v_fmamk_f32 v161, v161, 0x3e0293ee, v209
	v_max3_f32 v2, v2, v176, v160
	v_max3_f32 v4, v2, v177, v161
	s_mov_b64 s[8:9], 0
.LBB0_2768:
	s_andn2_b64 vcc, exec, s[8:9]
	v_mov_b32_e32 v2, 0
	s_cbranch_vccnz .LBB0_2770
	v_max_f32_e32 v4, v146, v146
	v_max_f32_e32 v5, v162, v162
	v_max_f32_e32 v4, v5, v4
	v_max3_f32 v4, v4, v163, v147
	v_max3_f32 v4, v4, v164, v148
	v_max3_f32 v4, v4, v165, v149
	v_max3_f32 v4, v4, v166, v150
	v_max3_f32 v4, v4, v167, v151
	v_max3_f32 v4, v4, v168, v152
	v_max3_f32 v4, v4, v169, v153
	v_max3_f32 v4, v4, v170, v154
	s_add_i32 s8, 0, 0x20000
	v_max3_f32 v4, v4, v171, v155
	v_mov_b32_e32 v2, s8
	v_max3_f32 v4, v4, v172, v156
	ds_read_b32 v2, v2
	v_max3_f32 v4, v4, v173, v157
	v_max3_f32 v4, v4, v174, v158
	v_max3_f32 v4, v4, v175, v159
	v_max3_f32 v4, v4, v176, v160
	v_max3_f32 v4, v4, v177, v161
	s_waitcnt lgkmcnt(0)
	v_fmamk_f32 v4, v4, 0x3e0293ee, v2
